# load balance: weight re-layout of the late-use tensors (layer-1 FFN, mLSTM projections) moved from the prologue into the idle slot of workgroups 128..255 at the end of the L0 in-projection phase
# speedup vs baseline: 1.0150x; 1.0076x over previous
; #define LAS __attribute__((address_space(3)))
; DI int ltid(int wv) { asm volatile("" : "+s"(wv)); int l = __builtin_amdgcn_mbcnt_hi(~0u, __builtin_amdgcn_mbcnt_lo(~0u, 0u)); asm volatile("" : "+v"(l)); return wv * 64 + l; }
; template <class F> DI void tr_items(const F& f, int Kdst, int Nrows, bf16_t* WT, LAS float* scr, int gw, int NGW, int lane, int& cum) {
;     const int nblk = Nrows / 32, nitems = (Kdst / 64) * nblk;
;     int first = (gw - cum) % NGW; if (first < 0) first += NGW; cum = (cum + nitems) % NGW;
;     for (int item = first; item < nitems; item += NGW) {
;         const int kb = item / nblk, nb = item % nblk, k0 = 64 * kb, n0 = 32 * nb;
; DI void phase_prologue(int wv, const ArgP a, LAS unsigned char* lds, int parts) {
;     unsigned char* ws = a.ws();
;     const int tid = ltid(wv), wave = tid >> 6, lane = tid & 63;
;     LAS float* scr = (LAS float*)(lds + wave * 8448);
;     const int gw = blockIdx.x * 8 + wave, NGW = gridDim.x * 8; int cum = 0;
;     if (parts & 1) {
;     { FW1 f{a.in(3), a.in(2)}; tr_items(f, 1024, 1536, (bf16_t*)(ws + O_W1T), scr, gw, NGW, lane, cum); }
.LBB0_15:
	s_mov_b32 s90, 0
.Lpro_entry:
	s_cmp_eq_u32 s90, 0
	s_cselect_b64 s[94:95], -1, 0
	s_cselect_b64 s[96:97], 0, -1
	v_mbcnt_lo_u32_b32 v0, -1, 0
	s_lshr_b32 s50, s48, 6
	v_mbcnt_hi_u32_b32 v192, -1, v0
	s_mov_b64 s[2:3], s[82:83]
	s_mov_b32 s0, s50
	v_mov_b32_e32 v14, v192
	s_load_dwordx2 s[12:13], s[2:3], 0xe8
	s_load_dword s24, s[82:83], 0xf8
	s_lshl_b32 s46, s80, 3
	s_cmp_eq_u32 s90, 1
	s_cselect_b32 s91, 0x400, 0
	s_sub_i32 s46, s46, s91
	s_add_u32 s88, s82, 0xf8
	s_addc_u32 s89, s83, 0
	v_lshl_add_u32 v15, s0, 6, v14
	s_waitcnt lgkmcnt(0)
	s_lshl_b32 s14, s24, 3
	s_cmp_eq_u32 s90, 1
	s_cselect_b32 s14, 0x400, s14
	s_abs_i32 s15, s14
	v_cvt_f32_u32_e32 v1, s15
	v_ashrrev_i32_e32 v0, 6, v15
	s_movk_i32 s0, 0x2100
	v_mul_lo_u32 v2, v0, s0
	v_rcp_iflag_f32_e32 v3, v1
	v_add_u32_e32 v20, 0, v2
	s_sub_i32 s0, 0, s15
	v_add_u32_e32 v0, s46, v0
	v_mul_f32_e32 v2, 0x4f7ffffe, v3
	v_cvt_u32_f32_e32 v2, v2
	v_sub_u32_e32 v3, 0, v0
	v_max_i32_e32 v3, v0, v3
	v_ashrrev_i32_e32 v1, 31, v0
	v_readfirstlane_b32 s25, v2
	s_mul_i32 s0, s0, s25
	s_mul_hi_u32 s0, s25, s0
	s_add_i32 s25, s25, s0
	v_mul_hi_u32 v2, v3, s25
	v_mul_lo_u32 v2, v2, s15
	v_sub_u32_e32 v2, v3, v2
	v_subrev_u32_e32 v3, s15, v2
	v_cmp_le_u32_e32 vcc, s15, v2
	v_and_b32_e32 v16, 63, v14
	s_movk_i32 s0, 0x300
	v_cndmask_b32_e32 v2, v2, v3, vcc
	v_subrev_u32_e32 v3, s15, v2
	v_cmp_le_u32_e32 vcc, s15, v2
	s_mul_hi_u32 s16, s25, 0x300
	v_and_b32_e32 v18, 31, v14
	v_cndmask_b32_e32 v2, v2, v3, vcc
	v_xor_b32_e32 v2, v2, v1
	v_sub_u32_e32 v2, v2, v1
	v_ashrrev_i32_e32 v3, 31, v2
	v_and_b32_e32 v3, s14, v3
	v_add_u32_e32 v10, v3, v2
	v_cmp_gt_i32_e32 vcc, s0, v10
	v_lshrrev_b32_e32 v17, 5, v16
	v_lshrrev_b32_e32 v19, 3, v16
	v_lshlrev_b32_e32 v21, 3, v16
	s_and_b64 vcc, vcc, s[94:95]
	s_and_saveexec_b64 s[0:1], vcc
	s_cbranch_execz .LBB0_82
	s_load_dwordx4 s[4:7], s[2:3], 0x10
	v_lshrrev_b32_e32 v13, 3, v16
	v_and_b32_e32 v2, 56, v21
	v_and_b32_e32 v11, 31, v14
	v_lshrrev_b32_e32 v12, 5, v16
	v_mul_u32_u24_e32 v5, 0x84, v2
	v_lshlrev_b32_e32 v2, 1, v2
	v_mov_b32_e32 v3, 0
	v_lshlrev_b32_e32 v6, 2, v13
	v_lshl_add_u32 v4, v11, 2, v20
	v_lshl_add_u64 v[2:3], s[12:13], 0, v[2:3]
	s_mov_b64 s[8:9], 0x3e0b000
	v_add3_u32 v22, v20, v5, v6
	v_mul_u32_u24_e32 v5, 0x84, v12
	v_lshl_add_u64 v[2:3], v[2:3], 0, s[8:9]
	v_lshlrev_b32_e32 v23, 5, v10
	s_lshl_b32 s17, s14, 5
	s_mov_b64 s[8:9], 0
	s_mov_b32 s18, 0x2aaaaaab
	s_movk_i32 s19, 0xfa00
	s_movk_i32 s20, 0x5a0
	s_movk_i32 s21, 0x1680
	v_add_u32_e32 v24, v4, v5
	s_movk_i32 s22, 0x2ff
	s_branch .LBB0_18

; template <class F> DI void tr_items(const F& f, int Kdst, int Nrows, bf16_t* WT, LAS float* scr, int gw, int NGW, int lane, int& cum) {
;     const int nblk = Nrows / 32, nitems = (Kdst / 64) * nblk;
;     int first = (gw - cum) % NGW; if (first < 0) first += NGW; cum = (cum + nitems) % NGW;
;     for (int item = first; item < nitems; item += NGW) {
; DI void phase_prologue(int wv, const ArgP a, LAS unsigned char* lds, int parts) {
;     ...
;     { FWQ f{a.in(12), a.in(11)}; tr_items(f, 256, 768, (bf16_t*)(ws + O_WQT), scr, gw, NGW, lane, cum); }
.LBB0_82:
	s_or_b64 exec, exec, s[0:1]
	s_mul_i32 s16, s16, s15
	s_sub_i32 s0, 0x300, s16
	s_sub_i32 s1, s0, s15
	s_cmp_ge_u32 s0, s15
	s_cselect_b32 s0, s1, s0
	s_sub_i32 s1, s0, s15
	s_cmp_ge_u32 s0, s15
	s_cselect_b32 s17, s1, s0
	v_subrev_u32_e32 v2, s17, v0
	v_sub_u32_e32 v4, 0, v2
	v_ashrrev_i32_e32 v3, 31, v2
	v_max_i32_e32 v2, v2, v4
	v_mul_hi_u32 v4, v2, s25
	v_mul_lo_u32 v4, v4, s15
	v_sub_u32_e32 v2, v2, v4
	v_subrev_u32_e32 v4, s15, v2
	v_cmp_le_u32_e32 vcc, s15, v2
	s_addk_i32 s17, 0x60
	s_movk_i32 s0, 0x60
	v_cndmask_b32_e32 v2, v2, v4, vcc
	v_subrev_u32_e32 v4, s15, v2
	v_cmp_le_u32_e32 vcc, s15, v2
	s_abs_i32 s11, s17
	s_movk_i32 s10, 0x300
	v_cndmask_b32_e32 v2, v2, v4, vcc
	v_xor_b32_e32 v2, v2, v3
	v_sub_u32_e32 v2, v2, v3
	v_ashrrev_i32_e32 v3, 31, v2
	v_and_b32_e32 v3, s14, v3
	v_add_u32_e32 v4, v3, v2
	s_mul_hi_u32 s16, s11, s25
	v_cmp_gt_i32_e32 vcc, s0, v4
	s_and_b64 vcc, vcc, s[94:95]
	s_and_saveexec_b64 s[0:1], vcc
	s_cbranch_execz .LBB0_85
	s_load_dwordx4 s[4:7], s[2:3], 0x58
	v_lshrrev_b32_e32 v5, 5, v16
	v_and_b32_e32 v6, 31, v14
	v_and_b32_e32 v2, 56, v21
	v_lshl_add_u32 v10, v6, 2, v20
	v_lshrrev_b32_e32 v7, 3, v16
	v_mul_u32_u24_e32 v8, 0x84, v2
	v_lshlrev_b32_e32 v2, 1, v2
	v_mov_b32_e32 v3, 0
	v_mul_u32_u24_e32 v11, 0x84, v5
	v_lshl_add_u64 v[2:3], s[12:13], 0, v[2:3]
	s_mov_b64 s[8:9], 0x410b000
	v_lshlrev_b32_e32 v9, 2, v7
	v_add_u32_e32 v10, v10, v11
	v_lshl_add_u64 v[2:3], v[2:3], 0, s[8:9]
	v_add3_u32 v8, v20, v8, v9
	v_lshlrev_b32_e32 v9, 5, v4
	s_lshl_b32 s18, s14, 5
	s_mov_b64 s[8:9], 0
	s_mov_b32 s19, 0x2aaaaaab
	s_movk_i32 s20, 0xfd00
	s_movk_i32 s21, 0xc00
	s_movk_i32 s22, 0x5f
	v_add_u32_e32 v11, 0x400, v10
	v_add_u32_e32 v12, 0x800, v10
	v_add_u32_e32 v13, 0xc00, v10
	v_add_u32_e32 v22, 0x1000, v10
	v_add_u32_e32 v23, 0x1400, v10
	v_add_u32_e32 v24, 0x1800, v10
	v_add_u32_e32 v25, 0x1c00, v10

; template <class F> DI void tr_items(const F& f, int Kdst, int Nrows, bf16_t* WT, LAS float* scr, int gw, int NGW, int lane, int& cum) {
;     const int nblk = Nrows / 32, nitems = (Kdst / 64) * nblk;
;     int first = (gw - cum) % NGW; if (first < 0) first += NGW; cum = (cum + nitems) % NGW;
;     for (int item = first; item < nitems; item += NGW) {
; DI void phase_prologue(int wv, const ArgP a, LAS unsigned char* lds, int parts) {
;     ...
;     { FWKV f{a.in(14), a.in(13), 0}; tr_items(f, 256, 512, (bf16_t*)(ws + O_WKT), scr, gw, NGW, lane, cum); }
.LBB0_85:
	s_or_b64 exec, exec, s[0:1]
	s_mul_i32 s16, s16, s15
	s_sub_i32 s1, s11, s16
	s_ashr_i32 s0, s17, 31
	s_sub_i32 s4, s1, s15
	s_cmp_ge_u32 s1, s15
	s_cselect_b32 s1, s4, s1
	s_sub_i32 s4, s1, s15
	s_cmp_ge_u32 s1, s15
	s_cselect_b32 s1, s4, s1
	s_xor_b32 s1, s1, s0
	s_sub_i32 s18, s1, s0
	v_subrev_u32_e32 v2, s18, v0
	v_sub_u32_e32 v4, 0, v2
	v_ashrrev_i32_e32 v3, 31, v2
	v_max_i32_e32 v2, v2, v4
	v_mul_hi_u32 v4, v2, s25
	v_mul_lo_u32 v4, v4, s15
	v_sub_u32_e32 v2, v2, v4
	v_subrev_u32_e32 v4, s15, v2
	v_cmp_le_u32_e32 vcc, s15, v2
	s_load_dwordx4 s[4:7], s[2:3], 0x68
	s_add_i32 s18, s18, 64
	v_cndmask_b32_e32 v2, v2, v4, vcc
	v_subrev_u32_e32 v4, s15, v2
	v_cmp_le_u32_e32 vcc, s15, v2
	s_abs_i32 s16, s18
	s_mul_hi_u32 s17, s16, s25
	v_cndmask_b32_e32 v2, v2, v4, vcc
	v_xor_b32_e32 v2, v2, v3
	v_sub_u32_e32 v2, v2, v3
	v_ashrrev_i32_e32 v3, 31, v2
	v_and_b32_e32 v3, s14, v3
	v_add_u32_e32 v22, v3, v2
	v_cmp_gt_i32_e32 vcc, 64, v22
	s_and_b64 vcc, vcc, s[94:95]
	s_and_saveexec_b64 s[0:1], vcc
	s_cbranch_execz .LBB0_152
	v_and_b32_e32 v2, 56, v21
	v_lshrrev_b32_e32 v25, 3, v16
	v_mul_u32_u24_e32 v7, 0x84, v2
	v_lshlrev_b32_e32 v2, 1, v2
	v_mov_b32_e32 v3, 0
	v_lshrrev_b32_e32 v23, 5, v16
	v_and_b32_e32 v24, 31, v14
	v_lshl_add_u64 v[4:5], s[12:13], 0, v[2:3]
	v_lshlrev_b32_e32 v2, 2, v25
	v_lshl_add_u32 v6, v24, 2, v20
	s_mov_b64 s[8:9], 0x416b000
	v_add3_u32 v26, v20, v7, v2
	v_mul_u32_u24_e32 v2, 0x84, v23
	v_lshl_add_u64 v[4:5], v[4:5], 0, s[8:9]
	v_lshlrev_b32_e32 v27, 5, v22
	s_lshl_b32 s19, s14, 5
	v_lshlrev_b32_e32 v28, 6, v22
	s_lshl_b32 s20, s14, 6
	s_mov_b64 s[8:9], 0
	s_movk_i32 s21, 0x80
	v_add_u32_e32 v29, v6, v2
	s_branch .LBB0_88

; template <class F> DI void tr_items(const F& f, int Kdst, int Nrows, bf16_t* WT, LAS float* scr, int gw, int NGW, int lane, int& cum) {
;     const int nblk = Nrows / 32, nitems = (Kdst / 64) * nblk;
;     int first = (gw - cum) % NGW; if (first < 0) first += NGW; cum = (cum + nitems) % NGW;
;     for (int item = first; item < nitems; item += NGW) {
; DI void phase_prologue(int wv, const ArgP a, LAS unsigned char* lds, int parts) {
;     ...
;     { FWKV f{a.in(14), a.in(13), 64}; tr_items(f, 256, 512, (bf16_t*)(ws + O_WVT), scr, gw, NGW, lane, cum); }
.LBB0_152:
	s_or_b64 exec, exec, s[0:1]
	s_mul_i32 s17, s17, s15
	s_sub_i32 s1, s16, s17
	s_ashr_i32 s0, s18, 31
	s_sub_i32 s8, s1, s15
	s_cmp_ge_u32 s1, s15
	s_cselect_b32 s1, s8, s1
	s_sub_i32 s8, s1, s15
	s_cmp_ge_u32 s1, s15
	s_cselect_b32 s1, s8, s1
	s_xor_b32 s1, s1, s0
	s_sub_i32 s18, s1, s0
	v_subrev_u32_e32 v2, s18, v0
	v_sub_u32_e32 v4, 0, v2
	v_ashrrev_i32_e32 v3, 31, v2
	v_max_i32_e32 v2, v2, v4
	v_mul_hi_u32 v4, v2, s25
	v_mul_lo_u32 v4, v4, s15
	v_sub_u32_e32 v2, v2, v4
	v_subrev_u32_e32 v4, s15, v2
	v_cmp_le_u32_e32 vcc, s15, v2
	s_add_i32 s18, s18, 64
	s_abs_i32 s16, s18
	v_cndmask_b32_e32 v2, v2, v4, vcc
	v_subrev_u32_e32 v4, s15, v2
	v_cmp_le_u32_e32 vcc, s15, v2
	s_mul_hi_u32 s17, s16, s25
	s_nop 0
	v_cndmask_b32_e32 v2, v2, v4, vcc
	v_xor_b32_e32 v2, v2, v3
	v_sub_u32_e32 v2, v2, v3
	v_ashrrev_i32_e32 v3, 31, v2
	v_and_b32_e32 v3, s14, v3
	v_add_u32_e32 v22, v3, v2
	v_cmp_gt_i32_e32 vcc, 64, v22
	s_and_b64 vcc, vcc, s[94:95]
	s_and_saveexec_b64 s[0:1], vcc
	s_cbranch_execz .LBB0_219
	v_and_b32_e32 v2, 56, v21
	v_lshrrev_b32_e32 v25, 3, v16
	v_mul_u32_u24_e32 v7, 0x84, v2
	v_lshlrev_b32_e32 v2, 1, v2
	v_mov_b32_e32 v3, 0
	v_lshrrev_b32_e32 v23, 5, v16
	v_and_b32_e32 v24, 31, v14
	v_lshl_add_u64 v[4:5], s[12:13], 0, v[2:3]
	v_lshlrev_b32_e32 v2, 2, v25
	v_lshl_add_u32 v6, v24, 2, v20
	s_mov_b64 s[8:9], 0x41ab000
	v_add3_u32 v26, v20, v7, v2
	v_mul_u32_u24_e32 v2, 0x84, v23
	v_lshl_add_u64 v[4:5], v[4:5], 0, s[8:9]
	v_lshlrev_b32_e32 v27, 5, v22
	s_lshl_b32 s19, s14, 5
	v_lshlrev_b32_e32 v28, 6, v22
	s_lshl_b32 s20, s14, 6
	s_mov_b64 s[8:9], 0
	s_movk_i32 s21, 0x80
	v_add_u32_e32 v29, v6, v2
	s_branch .LBB0_155

; template <class F> DI void tr_items(const F& f, int Kdst, int Nrows, bf16_t* WT, LAS float* scr, int gw, int NGW, int lane, int& cum) {
;     const int nblk = Nrows / 32, nitems = (Kdst / 64) * nblk;
;     int first = (gw - cum) % NGW; if (first < 0) first += NGW; cum = (cum + nitems) % NGW;
;     for (int item = first; item < nitems; item += NGW) {
; DI void phase_prologue(int wv, const ArgP a, LAS unsigned char* lds, int parts) {
;     ...
;     { FWRI f{a.in(6), a.in(8)}; tr_items(f, 512, 1024, (bf16_t*)(ws + O_WRIT), scr, gw, NGW, lane, cum); }
.LBB0_219:
	s_or_b64 exec, exec, s[0:1]
	s_mul_i32 s17, s17, s15
	s_sub_i32 s1, s16, s17
	s_ashr_i32 s0, s18, 31
	s_waitcnt lgkmcnt(0)
	s_sub_i32 s4, s1, s15
	s_cmp_ge_u32 s1, s15
	s_cselect_b32 s1, s4, s1
	s_sub_i32 s4, s1, s15
	s_cmp_ge_u32 s1, s15
	s_cselect_b32 s1, s4, s1
	s_xor_b32 s1, s1, s0
	s_sub_i32 s20, s1, s0
	v_subrev_u32_e32 v2, s20, v0
	v_sub_u32_e32 v4, 0, v2
	v_ashrrev_i32_e32 v3, 31, v2
	v_max_i32_e32 v2, v2, v4
	v_mul_hi_u32 v4, v2, s25
	v_mul_lo_u32 v4, v4, s15
	v_sub_u32_e32 v2, v2, v4
	v_subrev_u32_e32 v4, s15, v2
	v_cmp_le_u32_e32 vcc, s15, v2
	s_addk_i32 s20, 0x100
	s_movk_i32 s0, 0x100
	v_cndmask_b32_e32 v2, v2, v4, vcc
	v_subrev_u32_e32 v4, s15, v2
	v_cmp_le_u32_e32 vcc, s15, v2
	s_abs_i32 s18, s20
	s_mul_hi_u32 s19, s18, s25
	v_cndmask_b32_e32 v2, v2, v4, vcc
	v_xor_b32_e32 v2, v2, v3
	v_sub_u32_e32 v2, v2, v3
	v_ashrrev_i32_e32 v3, 31, v2
	v_and_b32_e32 v3, s14, v3
	v_add_u32_e32 v10, v3, v2
	v_cmp_gt_i32_e32 vcc, s0, v10
	s_and_b64 vcc, vcc, s[94:95]
	s_and_saveexec_b64 s[0:1], vcc
	s_cbranch_execz .LBB0_286
	s_load_dwordx2 s[6:7], s[2:3], 0x30
	s_load_dwordx2 s[8:9], s[2:3], 0x40
	v_and_b32_e32 v2, 56, v21
	v_lshrrev_b32_e32 v13, 3, v16
	v_mul_u32_u24_e32 v7, 0x84, v2
	v_lshlrev_b32_e32 v2, 1, v2
	v_mov_b32_e32 v3, 0
	v_and_b32_e32 v11, 31, v14
	v_lshrrev_b32_e32 v12, 5, v16
	v_lshl_add_u64 v[4:5], s[12:13], 0, v[2:3]
	v_lshlrev_b32_e32 v2, 2, v13
	v_lshl_add_u32 v6, v11, 2, v20
	s_mov_b64 s[4:5], 0x41eb000
	v_add3_u32 v22, v20, v7, v2
	v_mul_u32_u24_e32 v2, 0x84, v12
	v_lshl_add_u64 v[4:5], v[4:5], 0, s[4:5]
	v_lshlrev_b32_e32 v23, 5, v10
	s_lshl_b32 s21, s14, 5
	s_mov_b64 s[10:11], 0
	s_movk_i32 s22, 0x200
	v_add_u32_e32 v24, v6, v2
	s_movk_i32 s23, 0xff
	s_branch .LBB0_222

; template <class F> DI void tr_items(const F& f, int Kdst, int Nrows, bf16_t* WT, LAS float* scr, int gw, int NGW, int lane, int& cum) {
;     const int nblk = Nrows / 32, nitems = (Kdst / 64) * nblk;
;     int first = (gw - cum) % NGW; if (first < 0) first += NGW; cum = (cum + nitems) % NGW;
;     for (int item = first; item < nitems; item += NGW) {
; DI void phase_prologue(int wv, const ArgP a, LAS unsigned char* lds, int parts) {
;     ...
;     { FWP f{a.in(15), 1024}; tr_items(f, 1024, 1024, (bf16_t*)(ws + O_WO1T), scr, gw, NGW, lane, cum); }
.LBB0_286:
	s_or_b64 exec, exec, s[0:1]
	s_mul_i32 s19, s19, s15
	s_sub_i32 s1, s18, s19
	s_ashr_i32 s0, s20, 31
	s_sub_i32 s4, s1, s15
	s_cmp_ge_u32 s1, s15
	s_cselect_b32 s1, s4, s1
	s_sub_i32 s4, s1, s15
	s_cmp_ge_u32 s1, s15
	s_cselect_b32 s1, s4, s1
	s_xor_b32 s1, s1, s0
	s_sub_i32 s8, s1, s0
	v_subrev_u32_e32 v2, s8, v0
	v_sub_u32_e32 v4, 0, v2
	v_ashrrev_i32_e32 v3, 31, v2
	v_max_i32_e32 v2, v2, v4
	v_mul_hi_u32 v4, v2, s25
	v_mul_lo_u32 v4, v4, s15
	v_sub_u32_e32 v2, v2, v4
	v_subrev_u32_e32 v4, s15, v2
	v_cmp_le_u32_e32 vcc, s15, v2
	s_movk_i32 s0, 0x1ff
	s_nop 0
	v_cndmask_b32_e32 v2, v2, v4, vcc
	v_subrev_u32_e32 v4, s15, v2
	v_cmp_le_u32_e32 vcc, s15, v2
	s_nop 1
	v_cndmask_b32_e32 v2, v2, v4, vcc
	v_xor_b32_e32 v2, v2, v3
	v_sub_u32_e32 v2, v2, v3
	v_ashrrev_i32_e32 v3, 31, v2
	v_and_b32_e32 v3, s14, v3
	v_add_u32_e32 v13, v3, v2
	v_cmp_lt_i32_e32 vcc, s0, v13
	s_or_b64 vcc, vcc, s[96:97]
	s_and_saveexec_b64 s[0:1], vcc
	s_xor_b64 s[0:1], exec, s[0:1]
	s_cbranch_execz .LBB0_288
	v_lshrrev_b32_e32 v17, 5, v16
	v_lshrrev_b32_e32 v19, 3, v16
	v_and_b32_e32 v2, 56, v21
	v_and_b32_e32 v18, 31, v14
	v_mul_u32_u24_e32 v8, 0x84, v2
	v_mov_b32_e32 v3, 0
	v_mul_u32_u24_e32 v9, 0x84, v17
	v_or_b32_e32 v10, 8, v19
	v_or_b32_e32 v11, 16, v19
	v_or_b32_e32 v12, 24, v19

; template <class F> DI void tr_items(const F& f, int Kdst, int Nrows, bf16_t* WT, LAS float* scr, int gw, int NGW, int lane, int& cum) {
;     const int nblk = Nrows / 32, nitems = (Kdst / 64) * nblk;
;     int first = (gw - cum) % NGW; if (first < 0) first += NGW; cum = (cum + nitems) % NGW;
;     for (int item = first; item < nitems; item += NGW) {
; DI void phase_prologue(int wv, const ArgP a, LAS unsigned char* lds, int parts) {
;     ...
;     for (int l = 0; l < 2; ++l) {
;         { FWUP f{a.in(23) + (size_t)l * 1024 * 5632, a.in(22) + l * 1024}; tr_items(f, 1024, 5632, (bf16_t*)(ws + (l ? O_WUPT1 : O_WUPT0)), scr, gw, NGW, lane, cum); }
.LBB0_294:
	v_subrev_u32_e32 v4, s42, v0
	v_sub_u32_e32 v6, 0, v4
	v_ashrrev_i32_e32 v5, 31, v4
	v_max_i32_e32 v4, v4, v6
	v_mul_hi_u32 v6, v4, s25
	v_mul_lo_u32 v6, v6, s15
	v_sub_u32_e32 v4, v4, v6
	v_subrev_u32_e32 v6, s15, v4
	v_cmp_le_u32_e32 vcc, s15, v4
	s_nop 1
	v_cndmask_b32_e32 v4, v4, v6, vcc
	v_subrev_u32_e32 v6, s15, v4
	v_cmp_le_u32_e32 vcc, s15, v4
	s_nop 1
	v_cndmask_b32_e32 v4, v4, v6, vcc
	v_xor_b32_e32 v4, v4, v5
	v_sub_u32_e32 v4, v4, v5
	v_ashrrev_i32_e32 v5, 31, v4
	v_and_b32_e32 v5, s14, v5
	v_add_u32_e32 v7, v5, v4
	v_cmp_gt_i32_e32 vcc, s27, v7
	s_cmp_eq_u32 s43, s90
	s_cselect_b64 s[92:93], -1, 0
	s_and_b64 vcc, vcc, s[92:93]
	s_and_saveexec_b64 s[16:17], vcc
	s_cbranch_execz .LBB0_297
	s_mul_i32 s0, s43, 0x1600000
	s_waitcnt lgkmcnt(0)
	s_add_u32 s18, s10, s0
	s_addc_u32 s19, s11, 0
	s_lshl_b32 s0, s43, 10
	s_lshl_b64 s[4:5], s[0:1], 2
	s_add_u32 s20, s8, s4
	s_addc_u32 s21, s9, s5
	s_and_b64 s[4:5], s[6:7], exec
	s_cselect_b32 s0, 0x44eb000, 0
	v_lshl_add_u64 v[4:5], v[2:3], 0, s[0:1]
	v_lshlrev_b32_e32 v6, 5, v7
	v_lshlrev_b32_e32 v8, 4, v7
	s_mov_b64 s[22:23], 0

; template <class F> DI void tr_items(const F& f, int Kdst, int Nrows, bf16_t* WT, LAS float* scr, int gw, int NGW, int lane, int& cum) {
;     const int nblk = Nrows / 32, nitems = (Kdst / 64) * nblk;
;     int first = (gw - cum) % NGW; if (first < 0) first += NGW; cum = (cum + nitems) % NGW;
;     for (int item = first; item < nitems; item += NGW) {
; DI void phase_prologue(int wv, const ArgP a, LAS unsigned char* lds, int parts) {
;     ...
;         { FWP f{a.in(26) + (size_t)l * 2816 * 1024, 1024}; tr_items(f, 2816, 1024, (bf16_t*)(ws + (l ? O_WDNT1 : O_WDNT0)), scr, gw, NGW, lane, cum); }
.LBB0_297:
	s_or_b64 exec, exec, s[16:17]
	s_add_i32 s0, s42, 0xb00
	s_ashr_i32 s16, s0, 31
	s_abs_i32 s0, s0
	s_mul_hi_u32 s17, s0, s25
	s_mul_i32 s17, s17, s15
	s_sub_i32 s0, s0, s17
	s_xor_b64 s[4:5], s[6:7], -1
	s_sub_i32 s17, s0, s15
	s_cmp_ge_u32 s0, s15
	s_cselect_b32 s0, s17, s0
	s_sub_i32 s17, s0, s15
	s_cmp_ge_u32 s0, s15
	s_cselect_b32 s0, s17, s0
	s_xor_b32 s0, s0, s16
	s_sub_i32 s20, s0, s16
	v_subrev_u32_e32 v4, s20, v0
	v_sub_u32_e32 v6, 0, v4
	v_ashrrev_i32_e32 v5, 31, v4
	v_max_i32_e32 v4, v4, v6
	v_mul_hi_u32 v6, v4, s25
	v_mul_lo_u32 v6, v6, s15
	v_sub_u32_e32 v4, v4, v6
	v_subrev_u32_e32 v6, s15, v4
	v_cmp_le_u32_e32 vcc, s15, v4
	s_nop 1
	v_cndmask_b32_e32 v4, v4, v6, vcc
	v_subrev_u32_e32 v6, s15, v4
	v_cmp_le_u32_e32 vcc, s15, v4
	s_nop 1
	v_cndmask_b32_e32 v4, v4, v6, vcc
	v_xor_b32_e32 v4, v4, v5
	v_sub_u32_e32 v4, v4, v5
	v_ashrrev_i32_e32 v5, 31, v4
	v_and_b32_e32 v5, s14, v5
	v_add_u32_e32 v8, v5, v4
	v_cmp_gt_i32_e32 vcc, s37, v8
	s_cmp_eq_u32 s43, s90
	s_cselect_b64 s[92:93], -1, 0
	s_and_b64 vcc, vcc, s[92:93]
	s_and_saveexec_b64 s[16:17], vcc
	s_cbranch_execz .LBB0_293
	s_load_dwordx2 s[18:19], s[2:3], 0xd0
	s_mul_i32 s0, s43, 0xb00000
	v_mul_lo_u32 v34, v8, s39
	s_mul_i32 s21, s14, 0x16000
	v_lshl_add_u32 v35, v8, 5, v18
	s_waitcnt lgkmcnt(0)
	s_add_u32 s18, s18, s0
	s_addc_u32 s19, s19, 0
	s_and_b64 s[6:7], s[6:7], exec
	s_cselect_b32 s0, s38, 0xb00000
	v_lshl_add_u64 v[4:5], v[2:3], 0, s[0:1]
	s_mov_b64 s[6:7], 0

; template <class F> DI void tr_items(const F& f, int Kdst, int Nrows, bf16_t* WT, LAS float* scr, int gw, int NGW, int lane, int& cum) {
;     const int nblk = Nrows / 32, nitems = (Kdst / 64) * nblk;
;     int first = (gw - cum) % NGW; if (first < 0) first += NGW; cum = (cum + nitems) % NGW;
;     for (int item = first; item < nitems; item += NGW) {
; DI void phase_prologue(int wv, const ArgP a, LAS unsigned char* lds, int parts) {
;     ...
;     { FWOIN f{a.in(17), a.in(16)}; tr_items(f, 1024, 3072, (bf16_t*)(ws + O_WOINT), scr, gw, NGW, lane, cum); }
.LBB0_300:
	v_subrev_u32_e32 v4, s42, v0
	v_sub_u32_e32 v6, 0, v4
	v_ashrrev_i32_e32 v5, 31, v4
	v_max_i32_e32 v4, v4, v6
	v_mul_hi_u32 v6, v4, s25
	v_mul_lo_u32 v6, v6, s15
	v_sub_u32_e32 v4, v4, v6
	v_subrev_u32_e32 v6, s15, v4
	v_cmp_le_u32_e32 vcc, s15, v4
	s_add_i32 s16, s42, 0x600
	s_movk_i32 s17, 0x600
	v_cndmask_b32_e32 v4, v4, v6, vcc
	v_subrev_u32_e32 v6, s15, v4
	v_cmp_le_u32_e32 vcc, s15, v4
	s_waitcnt lgkmcnt(0)
	s_abs_i32 s10, s16
	s_mul_hi_u32 s11, s10, s25
	v_cndmask_b32_e32 v4, v4, v6, vcc
	v_xor_b32_e32 v4, v4, v5
	v_sub_u32_e32 v4, v4, v5
	v_ashrrev_i32_e32 v5, 31, v4
	v_and_b32_e32 v5, s14, v5
	v_add_u32_e32 v7, v5, v4
	v_cmp_gt_i32_e32 vcc, s17, v7
	s_and_b64 vcc, vcc, s[96:97]
	s_and_saveexec_b64 s[0:1], vcc
	s_cbranch_execz .LBB0_303
	s_load_dwordx4 s[4:7], s[2:3], 0x80
	s_mov_b64 s[8:9], 0x1080000
	v_lshl_add_u64 v[4:5], v[2:3], 0, s[8:9]
	v_lshlrev_b32_e32 v6, 5, v7
	s_mov_b64 s[8:9], 0
	s_mov_b32 s18, 0x2aaaaaab
	s_movk_i32 s19, 0xf400
	s_movk_i32 s20, 0x200
	v_mov_b32_e32 v24, 0xfffffc00
	v_mov_b32_e32 v25, 0x600
	v_mov_b32_e32 v26, 0x3db504f3
	s_movk_i32 s21, 0x3020
	s_waitcnt lgkmcnt(0)
	v_mov_b64_e32 v[8:9], s[6:7]
	s_movk_i32 s6, 0x5ff
	v_add_u32_e32 v27, 0x400, v20
	v_add_u32_e32 v28, 0x800, v20
	v_add_u32_e32 v29, 0xc00, v20
	v_add_u32_e32 v30, 0x1000, v20
	v_add_u32_e32 v31, 0x1400, v20
	v_add_u32_e32 v32, 0x1800, v20
	v_add_u32_e32 v33, 0x1c00, v20

; template <class F> DI void tr_items(const F& f, int Kdst, int Nrows, bf16_t* WT, LAS float* scr, int gw, int NGW, int lane, int& cum) {
;     const int nblk = Nrows / 32, nitems = (Kdst / 64) * nblk;
;     int first = (gw - cum) % NGW; if (first < 0) first += NGW; cum = (cum + nitems) % NGW;
;     for (int item = first; item < nitems; item += NGW) {
; DI void phase_prologue(int wv, const ArgP a, LAS unsigned char* lds, int parts) {
;     ...
;     { FWP f{a.in(21), 1024}; tr_items(f, 1024, 1024, (bf16_t*)(ws + O_WO2T), scr, gw, NGW, lane, cum); }
.LBB0_303:
	s_or_b64 exec, exec, s[0:1]
	s_mul_i32 s11, s11, s15
	s_sub_i32 s1, s10, s11
	s_ashr_i32 s0, s16, 31
	s_sub_i32 s4, s1, s15
	s_cmp_ge_u32 s1, s15
	s_cselect_b32 s1, s4, s1
	s_sub_i32 s4, s1, s15
	s_cmp_ge_u32 s1, s15
	s_cselect_b32 s1, s4, s1
	s_xor_b32 s1, s1, s0
	s_sub_i32 s0, s0, s1
	v_add_u32_e32 v4, s0, v0
	v_sub_u32_e32 v6, 0, v4
	v_ashrrev_i32_e32 v5, 31, v4
	v_max_i32_e32 v4, v4, v6
	v_mul_hi_u32 v6, v4, s25
	v_mul_lo_u32 v6, v6, s15
	v_sub_u32_e32 v4, v4, v6
	v_subrev_u32_e32 v6, s15, v4
	v_cmp_le_u32_e32 vcc, s15, v4
	s_movk_i32 s0, 0x200
	s_nop 0
	v_cndmask_b32_e32 v4, v4, v6, vcc
	v_subrev_u32_e32 v6, s15, v4
	v_cmp_le_u32_e32 vcc, s15, v4
	s_nop 1
	v_cndmask_b32_e32 v4, v4, v6, vcc
	v_xor_b32_e32 v4, v4, v5
	v_sub_u32_e32 v4, v4, v5
	v_ashrrev_i32_e32 v5, 31, v4
	v_and_b32_e32 v5, s14, v5
	v_add_u32_e32 v6, v5, v4
	v_cmp_gt_i32_e32 vcc, s0, v6
	s_and_b64 vcc, vcc, s[96:97]
	s_and_saveexec_b64 s[0:1], vcc
	s_cbranch_execz .LBB0_306
	s_load_dwordx2 s[4:5], s[2:3], 0xa8
	s_mov_b64 s[6:7], 0x1680000
	v_lshl_add_u64 v[2:3], v[2:3], 0, s[6:7]
	v_lshlrev_b32_e32 v7, 5, v6
	s_mov_b64 s[6:7], 0
	s_movk_i32 s8, 0x1ff
	v_add_u32_e32 v8, 0x400, v20
	v_add_u32_e32 v9, 0x800, v20
	v_add_u32_e32 v24, 0xc00, v20
	v_add_u32_e32 v25, 0x1000, v20
	v_add_u32_e32 v26, 0x1400, v20
	v_add_u32_e32 v27, 0x1800, v20
	v_add_u32_e32 v28, 0x1c00, v20

; DI void phase_prologue(int wv, const ArgP a, LAS unsigned char* lds, int parts) {
;     ...
;     if (parts & 2) {
;     const float* x = a.in(0); bf16_t* XB = (bf16_t*)(ws + O_XB) + 2 * 1024; u64* rowss = (u64*)(ws + O_ROWSS);
; #pragma unroll 4
;     for (int t = gw; t < S; t += NGW) {
.LBB0_306:
	s_or_b64 exec, exec, s[0:1]
	s_movk_i32 s0, 0x4000
	v_cmp_gt_i32_e32 vcc, s0, v0
	v_and_b32_e32 v196, 64, v192
	v_xor_b32_e32 v157, 1, v192
	v_xor_b32_e32 v156, 2, v192
	v_xor_b32_e32 v155, 4, v192
	v_xor_b32_e32 v154, 8, v192
	v_xor_b32_e32 v153, 16, v192
	v_xor_b32_e32 v152, 32, v192
	s_and_b64 vcc, vcc, s[94:95]
	s_and_saveexec_b64 s[0:1], vcc
	s_cbranch_execz .LBB0_313
	v_add_u32_e32 v2, 64, v196
	v_cmp_lt_i32_e32 vcc, v157, v2
	s_load_dwordx2 s[16:17], s[2:3], 0x0
	v_lshlrev_b64 v[10:11], 12, v[0:1]
	v_cndmask_b32_e32 v3, v192, v157, vcc
	v_cmp_lt_i32_e32 vcc, v156, v2
	v_lshlrev_b32_e32 v12, 2, v3
	v_lshl_or_b32 v10, v16, 4, v10
	v_cndmask_b32_e32 v3, v192, v156, vcc
	v_cmp_lt_i32_e32 vcc, v155, v2
	v_lshlrev_b32_e32 v13, 2, v3
	s_ashr_i32 s15, s14, 31
	v_cndmask_b32_e32 v3, v192, v155, vcc
	v_cmp_lt_i32_e32 vcc, v154, v2
	v_lshlrev_b32_e32 v17, 2, v3
	v_lshlrev_b32_e32 v4, 17, v16
	v_cndmask_b32_e32 v3, v192, v154, vcc
	v_cmp_lt_i32_e32 vcc, v153, v2
	v_lshlrev_b32_e32 v18, 2, v3
	v_mov_b32_e32 v5, 0
	v_cndmask_b32_e32 v3, v192, v153, vcc
	v_cmp_lt_i32_e32 vcc, v152, v2
	v_lshlrev_b32_e32 v19, 2, v3
	v_lshlrev_b64 v[8:9], 11, v[0:1]
	v_cndmask_b32_e32 v2, v192, v152, vcc
	v_lshlrev_b32_e32 v20, 2, v2
	v_subrev_co_u32_e64 v2, s[4:5], 1, v16
	v_cmp_gt_u32_e64 s[6:7], 4, v2
	v_mov_b64_e32 v[2:3], 0x1880000
	v_lshl_add_u64 v[2:3], v[0:1], 3, v[2:3]
	s_waitcnt lgkmcnt(0)
	v_lshl_add_u64 v[10:11], s[16:17], 0, v[10:11]
	s_mov_b64 s[16:17], 0x800
	s_lshl_b64 s[8:9], s[14:15], 3
	v_lshl_add_u64 v[6:7], v[2:3], 0, v[4:5]
	v_lshl_or_b32 v8, v16, 3, v8
	s_lshl_b64 s[10:11], s[14:15], 11
	v_lshl_add_u64 v[10:11], v[10:11], 0, s[16:17]
	s_lshl_b64 s[16:17], s[14:15], 12
	s_mov_b64 s[18:19], 0
	s_mov_b32 s15, 0x1d88000
	s_movk_i32 s22, 0x3fff
	v_mov_b32_e32 v4, v5
	s_branch .LBB0_309

; DI void phase_prologue(int wv, const ArgP a, LAS unsigned char* lds, int parts) {
;     ...
;     if (parts & 4) {
;     const int* pos = (const int*)a.in(1); float* cst = (float*)(ws + O_CSTAB);
;     for (int e = blockIdx.x * 512 + tid; e < S * 16; e += gridDim.x * 512) { const int t = e >> 4, i = e & 15;
.LBB0_313:
	s_or_b64 exec, exec, s[0:1]
	s_lshl_b32 s33, s80, 9
	v_add_u32_e32 v2, s33, v15
	s_mov_b32 s0, 0x40000
	v_cmp_gt_i32_e32 vcc, s0, v2
	s_and_b64 vcc, vcc, s[94:95]
	s_and_saveexec_b64 s[0:1], vcc
	s_cbranch_execz .LBB0_316
	v_and_b32_e32 v0, 15, v14
	v_cvt_f32_ubyte0_e32 v0, v0
	s_load_dwordx2 s[2:3], s[2:3], 0x8
	v_mul_f32_e32 v0, 0xbf549a78, v0
	v_exp_f32_e32 v3, v0
	s_add_u32 s4, s12, 0x1940000
	s_addc_u32 s5, s13, 0
	s_lshl_b32 s8, s24, 9
	v_lshlrev_b32_e32 v0, 1, v2
	s_lshl_b32 s9, s24, 10
	s_mov_b64 s[6:7], 0
	s_mov_b32 s10, 0x3ffff

; #define LAS __attribute__((address_space(3)))
; DI int ltid(int wv) { asm volatile("" : "+s"(wv)); int l = __builtin_amdgcn_mbcnt_hi(~0u, __builtin_amdgcn_mbcnt_lo(~0u, 0u)); asm volatile("" : "+v"(l)); return wv * 64 + l; }
; DI unsigned xb_xcc_id() { return (unsigned)__builtin_amdgcn_s_getreg((3 << 11) | 20) & 0xFu; }
; DI void xcd_barrier(int wv, unsigned* bar, volatile LAS unsigned* st) {
;     asm volatile("s_waitcnt vmcnt(0)" ::: "memory");
;     __syncthreads();
;     if (ltid(wv) == 0) {
;         const unsigned x = xb_xcc_id();
;         __builtin_amdgcn_s_waitcnt(0);
;         unsigned nloc = st[0], nx = st[1];
;         if (nloc == 0u) { xcd_barrier_complete(bar, x, nloc, nx); st[0] = nloc; st[1] = nx; }
.LBB0_316:
	s_or_b64 exec, exec, s[0:1]
	s_cmp_eq_u32 s90, 1
	s_cbranch_scc1 .Lslot_return
	s_mov_b64 s[2:3], s[82:83]
	s_mov_b32 s0, s50
	s_waitcnt vmcnt(0)
	s_waitcnt lgkmcnt(0)
	s_barrier
	s_lshl_b32 s0, s0, 6
	v_mov_b32_e32 v0, v192
	s_sub_i32 s0, 0, s0
	s_nop 0
	v_cmp_eq_u32_e32 vcc, s0, v0
	s_and_saveexec_b64 s[0:1], vcc
	s_xor_b64 s[0:1], exec, s[0:1]
	v_writelane_b32 v240, s50, 0
	s_cbranch_execz .LBB0_369
	s_add_i32 s5, 0, 0x22000
	v_mov_b32_e32 v0, s5
	s_load_dwordx2 s[2:3], s[2:3], 0xe8
	s_getreg_b32 s4, hwreg(HW_REG_XCC_ID, 0, 4)
	s_waitcnt vmcnt(0) expcnt(0) lgkmcnt(0)
	ds_read_b32 v2, v0
	s_add_i32 s5, 0, 0x22004
	v_mov_b32_e32 v0, s5
	ds_read_b32 v0, v0
	s_and_b32 s47, s4, 15
	s_waitcnt lgkmcnt(1)
	v_cmp_ne_u32_e32 vcc, 0, v2
	s_cbranch_vccnz .LBB0_332
	s_add_u32 s4, s2, 0x1d83200
	s_addc_u32 s5, s3, 0
	s_add_u32 s6, s2, 0x1d83400
	s_addc_u32 s7, s3, 0
	s_add_u32 s8, s2, 0x1d83500
	s_addc_u32 s9, s3, 0
	s_add_u32 s10, s2, 0x1d83600
	s_addc_u32 s11, s3, 0
	s_add_u32 s12, s2, 0x1d83700
	s_addc_u32 s13, s3, 0
	s_add_u32 s14, s2, 0x1d83800
	s_addc_u32 s15, s3, 0
	s_add_u32 s16, s2, 0x1d83900
	s_addc_u32 s17, s3, 0
	s_add_u32 s18, s2, 0x1d83a00
	s_addc_u32 s19, s3, 0
	s_add_u32 s20, s2, 0x1d83b00
	s_addc_u32 s21, s3, 0
	s_add_u32 s22, s2, 0x1d83c00
	s_addc_u32 s23, s3, 0
	s_add_u32 s24, s2, 0x1d83d00
	s_addc_u32 s25, s3, 0
	s_add_u32 s26, s2, 0x1d83e00
	s_addc_u32 s27, s3, 0
	s_add_u32 s28, s2, 0x1d83f00
	s_addc_u32 s29, s3, 0
	s_add_u32 s30, s2, 0x1d84000
	s_addc_u32 s31, s3, 0
	s_add_u32 s34, s2, 0x1d84100
	s_load_dword s49, s[88:89], 0x0
	s_addc_u32 s35, s3, 0
	s_add_u32 s36, s2, 0x1d84200
	s_addc_u32 s37, s3, 0
	s_add_u32 s38, s2, 0x1d84300
	s_addc_u32 s39, s3, 0
	s_mov_b32 s50, 1
	v_mov_b32_e32 v16, 0
	s_branch .LBB0_320

; #define WSB (getargs().ws())
; #define GSYNC() xcd_barrier(wv, BARW, BARST)
; __global__ void __launch_bounds__(512, 2) fwd_kernel(Args a_unused) {
;     ...
;       pg8::gemm_phase<false>(wv, lds, XBP, 1024, (const bf16_t*)(WSB + O_W1T), 1024, 1024, 64, 6, E); }
;     }
;     ...
;     GSYNC();
.LBB0_388:
	s_cmpk_lt_u32 s80, 0x80
	s_cbranch_scc1 .Lslot_skip
	s_barrier
	s_mov_b32 s90, 1
	s_branch .Lpro_entry
.Lslot_return:
	s_lshl_b32 s46, s80, 3
